# scan chunk loop: chunk-start barrier kept only for chunk 0 (later chunks are already ordered by the barriers after the LDS fill and after the 16 steps)
# speedup vs baseline: 1.0319x; 1.0023x over previous
; DI float lo_bf(unsigned u) { bfx2 h = __builtin_bit_cast(bfx2, u); return (float)h[0]; }
; DI float hi_bf(unsigned u) { bfx2 h = __builtin_bit_cast(bfx2, u); return (float)h[1]; }
; DI float row16_sum(float v) { v += dpp_f<0x128>(v); v += dpp_f<0x124>(v); v += dpp_f<0x122>(v); v += dpp_f<0x121>(v); return v; }
; DI void scan_item(const Params& p, int b, int h, int half, char* smem, unsigned* pgen, unsigned kp) {
;     ...
;   auto convert = [&](const ScanRaw& R) {
;     const float4 mu_r = *(const float4*)(CT + lc);
;     const float4 mu_v = *(const float4*)(CT + 64 + lc);
;     const float4 rk = *(const float4*)(CT + 128 + lc);
;     pw = R.w; pk = R.k; pkk = R.kk; pa = R.a;
;     float c0, p0;
;     c0 = lo_bf(R.rc.x); p0 = lo_bf(R.rp.x); pr.x = c0 + (p0 - c0) * mu_r.x;
;     c0 = hi_bf(R.rc.x); p0 = hi_bf(R.rp.x); pr.y = c0 + (p0 - c0) * mu_r.y;
;     c0 = lo_bf(R.rc.y); p0 = lo_bf(R.rp.y); pr.z = c0 + (p0 - c0) * mu_r.z;
;     c0 = hi_bf(R.rc.y); p0 = hi_bf(R.rp.y); pr.w = c0 + (p0 - c0) * mu_r.w;
;     c0 = lo_bf(R.vc.x); p0 = lo_bf(R.vp.x); pv.x = c0 + (p0 - c0) * mu_v.x;
;     c0 = hi_bf(R.vc.x); p0 = hi_bf(R.vp.x); pv.y = c0 + (p0 - c0) * mu_v.y;
;     c0 = lo_bf(R.vc.y); p0 = lo_bf(R.vp.y); pv.z = c0 + (p0 - c0) * mu_v.z;
;     c0 = hi_bf(R.vc.y); p0 = hi_bf(R.vp.y); pv.w = c0 + (p0 - c0) * mu_v.w;
;     pbon = row16_sum(pr.x * pk.x * rk.x + pr.y * pk.y * rk.y + pr.z * pk.z * rk.z + pr.w * pk.w * rk.w);
;   };
;     ...
;     __syncthreads();
;     convert(R);
;     if (c == 0 && ls == 0) override_t0();
.LBB0_687:
	s_waitcnt lgkmcnt(0)
	s_cmp_lg_u32 s25, 0
	s_cbranch_scc1 .Lscan_skip_b1
	s_barrier
.Lscan_skip_b1:
	ds_read_b128 v[38:41], v193 offset:28928
	s_waitcnt vmcnt(9)
	v_cvt_f32_f16_e32 v0, v116
	v_cvt_f32_f16_e32 v34, v130
	v_cvt_f32_f16_sdwa v46, v116 dst_sel:DWORD dst_unused:UNUSED_PAD src0_sel:WORD_1
	v_cvt_f32_f16_sdwa v47, v130 dst_sel:DWORD dst_unused:UNUSED_PAD src0_sel:WORD_1
	ds_read_b128 v[42:45], v193 offset:29440
	v_sub_f32_e32 v0, v34, v0
	ds_read_b128 v[34:37], v193 offset:29184
	s_waitcnt lgkmcnt(2)
	v_fma_mix_f32 v38, v0, v38, v116 op_sel_hi:[0,0,1]
	v_sub_f32_e32 v0, v47, v46
	v_cvt_f32_f16_e32 v46, v117
	v_cvt_f32_f16_e32 v47, v131
	v_cvt_f32_f16_sdwa v48, v117 dst_sel:DWORD dst_unused:UNUSED_PAD src0_sel:WORD_1
	v_cvt_f32_f16_sdwa v49, v131 dst_sel:DWORD dst_unused:UNUSED_PAD src0_sel:WORD_1
	v_fma_mix_f32 v39, v0, v39, v116 op_sel:[0,0,1] op_sel_hi:[0,0,1]
	v_sub_f32_e32 v0, v47, v46
	v_fma_mix_f32 v40, v0, v40, v117 op_sel_hi:[0,0,1]
	v_sub_f32_e32 v0, v49, v48
	v_mul_f32_e32 v46, v7, v39
	v_fma_mix_f32 v41, v0, v41, v117 op_sel:[0,0,1] op_sel_hi:[0,0,1]
	v_mul_f32_e32 v0, v6, v38
	s_waitcnt lgkmcnt(1)
	v_mul_f32_e32 v46, v46, v43
	v_fmac_f32_e32 v46, v0, v42
	v_mul_f32_e32 v0, v8, v40
	v_fmac_f32_e32 v46, v0, v44
	v_mul_f32_e32 v0, v9, v41
	v_fmac_f32_e32 v46, v0, v45
	s_cmp_eq_u32 s25, 0
	v_readlane_b32 s16, v252, 54
	v_add_f32_dpp v0, v46, v46 row_ror:8 row_mask:0xf bank_mask:0xf bound_ctrl:1
	s_cselect_b64 s[4:5], -1, 0
	v_readlane_b32 s17, v252, 55
	v_add_f32_dpp v0, v0, v0 row_ror:4 row_mask:0xf bank_mask:0xf bound_ctrl:1
	v_mov_b64_e32 v[56:57], v[28:29]
	v_mov_b64_e32 v[52:53], v[12:13]
	v_add_f32_dpp v0, v0, v0 row_ror:2 row_mask:0xf bank_mask:0xf bound_ctrl:1
	v_mov_b64_e32 v[48:49], v[8:9]
	s_and_b64 s[16:17], s[16:17], s[4:5]
	v_add_f32_dpp v0, v0, v0 row_ror:1 row_mask:0xf bank_mask:0xf bound_ctrl:1
	v_mov_b64_e32 v[54:55], v[26:27]
	v_mov_b64_e32 v[50:51], v[10:11]
	v_mov_b64_e32 v[46:47], v[6:7]
	s_and_saveexec_b64 s[4:5], s[16:17]
	s_cbranch_execz .LBB0_691
	global_load_dwordx4 v[38:41], v[124:125], off
	global_load_dwordx4 v[46:49], v[124:125], off offset:2048
	global_load_dwordx4 v[50:53], v[132:133], off
	v_readlane_b32 s18, v253, 0
	s_mov_b64 s[16:17], 0
	v_readlane_b32 s19, v253, 1

; DI float* aaptr(char* ws, size_t m) { return (float*)(ws + OFF_PROJ + (m >> 12) * SLAB + PROJ_B) + (m & 4095) * 512; }
; DI void scan_item(const Params& p, int b, int h, int half, char* smem, unsigned* pgen, unsigned kp) {
;     ...
;   auto prefetch = [&](int c, ScanRaw& R) {
;     const int t = c * SC + ls;
;     const size_t m = (size_t)b * T + t;
;     R.w = *(const float4*)(Wg + m * 512 + hc);
;     R.k = *(const float4*)(KPg + m * 512 + hc);
;     R.kk = *(const float4*)(KKg + m * 512 + hc);
;     R.a = *(const float4*)(aaptr(p.ws, m) + hc);
;     R.rc = *(const uint2*)(proj + prow(m) + R_OFF + hc);
;     R.vc = *(const uint2*)(proj + prow(m) + V_OFF + hc);
;     R.rp = make_uint2(0, 0); R.vp = make_uint2(0, 0);
;     if (t > 0) { R.rp = *(const uint2*)(proj + prow(m - 1) + R_OFF + hc); R.vp = *(const uint2*)(proj + prow(m - 1) + V_OFF + hc); }
;   };
;     ...
;     __syncthreads();
;     convert(R);
;     if (c == 0 && ls == 0) override_t0();
;     *(float4*)(Rl + ls * 64 + lc) = pr;
;     *(float4*)(Wl + ls * 64 + lc) = pw;
;     *(float4*)(Kl + ls * 64 + lc) = pk;
;     *(float4*)(Vl + ls * 64 + lc) = pv;
;     *(float4*)(Al + ls * 64 + lc) = make_float4(-pkk.x, -pkk.y, -pkk.z, -pkk.w);
;     *(float4*)(Bl + ls * 64 + lc) = make_float4(pkk.x * pa.x, pkk.y * pa.y, pkk.z * pa.z, pkk.w * pa.w);
;     if ((tid & 15) == 0) BON[ls] = pbon;
;     __syncthreads();
.LBB0_707:
	s_or_b64 exec, exec, s[18:19]
	ds_read_b128 v[34:37], v193 offset:29440
	ds_read_b128 v[38:41], v193 offset:28928
	s_waitcnt vmcnt(5)
	v_cvt_f32_f16_sdwa v43, v140 dst_sel:DWORD dst_unused:UNUSED_PAD src0_sel:WORD_1
	v_cvt_f32_f16_e32 v42, v140
	s_waitcnt vmcnt(3)
	v_cvt_f32_f16_sdwa v45, v146 dst_sel:DWORD dst_unused:UNUSED_PAD src0_sel:WORD_1
	v_cvt_f32_f16_e32 v44, v146
	v_pk_add_f32 v[44:45], v[44:45], v[42:43] neg_lo:[0,1] neg_hi:[0,1]
	s_waitcnt lgkmcnt(0)
	v_pk_fma_f32 v[38:39], v[44:45], v[38:39], v[42:43]
	v_cvt_f32_f16_sdwa v43, v141 dst_sel:DWORD dst_unused:UNUSED_PAD src0_sel:WORD_1
	v_cvt_f32_f16_e32 v42, v141
	v_cvt_f32_f16_sdwa v45, v147 dst_sel:DWORD dst_unused:UNUSED_PAD src0_sel:WORD_1
	v_cvt_f32_f16_e32 v44, v147
	v_pk_add_f32 v[44:45], v[44:45], v[42:43] neg_lo:[0,1] neg_hi:[0,1]
	s_nop 0
	v_pk_fma_f32 v[40:41], v[44:45], v[40:41], v[42:43]
	v_mul_f32_e32 v43, v19, v39
	v_mul_f32_e32 v42, v18, v38
	v_mul_f32_e32 v35, v43, v35
	v_fmac_f32_e32 v35, v42, v34
	v_mul_f32_e32 v34, v20, v40
	v_fmac_f32_e32 v35, v34, v36
	v_mul_f32_e32 v34, v21, v41
	ds_write_b128 v195, v[38:41]
	ds_write_b128 v195, v[14:17] offset:4096
	ds_write_b128 v195, v[18:21] offset:8192
	v_fmac_f32_e32 v35, v34, v37
	ds_read_b128 v[36:39], v193 offset:29184
	v_cvt_f32_f16_sdwa v41, v144 dst_sel:DWORD dst_unused:UNUSED_PAD src0_sel:WORD_1
	v_cvt_f32_f16_e32 v40, v144
	s_waitcnt vmcnt(2)
	v_cvt_f32_f16_sdwa v43, v148 dst_sel:DWORD dst_unused:UNUSED_PAD src0_sel:WORD_1
	v_cvt_f32_f16_e32 v42, v148
	v_add_f32_dpp v34, v35, v35 row_ror:8 row_mask:0xf bank_mask:0xf bound_ctrl:1
	v_mov_b32_e32 v35, 0
	v_pk_add_f32 v[42:43], v[42:43], v[40:41] neg_lo:[0,1] neg_hi:[0,1]
	s_waitcnt lgkmcnt(0)
	v_pk_fma_f32 v[36:37], v[42:43], v[36:37], v[40:41]
	v_cvt_f32_f16_sdwa v41, v145 dst_sel:DWORD dst_unused:UNUSED_PAD src0_sel:WORD_1
	v_cvt_f32_f16_e32 v40, v145
	v_cvt_f32_f16_sdwa v43, v149 dst_sel:DWORD dst_unused:UNUSED_PAD src0_sel:WORD_1
	v_cvt_f32_f16_e32 v42, v149
	v_add_f32_dpp v34, v34, v34 row_ror:4 row_mask:0xf bank_mask:0xf bound_ctrl:1
	v_pk_add_f32 v[42:43], v[42:43], v[40:41] neg_lo:[0,1] neg_hi:[0,1]
	s_nop 0
	v_pk_fma_f32 v[38:39], v[42:43], v[38:39], v[40:41]
	v_add_f32_dpp v34, v34, v34 row_ror:2 row_mask:0xf bank_mask:0xf bound_ctrl:1
	ds_write_b128 v195, v[36:39] offset:12288
	v_xor_b32_e32 v39, 0x80000000, v25
	v_xor_b32_e32 v38, 0x80000000, v24
	v_xor_b32_e32 v37, 0x80000000, v23
	v_xor_b32_e32 v36, 0x80000000, v22
	v_mov_b32_dpp v35, v34 row_ror:1 row_mask:0xf bank_mask:0xf
	ds_write_b128 v195, v[36:39] offset:16384
	v_pk_mul_f32 v[38:39], v[24:25], v[32:33]
	v_pk_mul_f32 v[36:37], v[22:23], v[30:31]
	ds_write_b128 v195, v[36:39] offset:20480
	s_mov_b64 s[18:19], exec
	v_readlane_b32 s26, v252, 36
	v_readlane_b32 s27, v252, 37
	s_and_b64 s[26:27], s[18:19], s[26:27]
	s_mov_b64 exec, s[26:27]
	v_add_f32_e32 v34, v34, v35
	ds_write_b32 v171, v34 offset:28672
	s_or_b64 exec, exec, s[18:19]
	s_andn2_b64 vcc, exec, s[4:5]
	s_waitcnt lgkmcnt(0)
	s_barrier
	s_cbranch_vccnz .LBB0_711
	v_add_u32_e32 v0, 48, v0
	v_lshl_add_u64 v[34:35], s[6:7], 0, v[0:1]
	v_alignbit_b32 v0, v35, v34, 12
	v_mov_b64_e32 v[30:31], s[94:95]
	s_mov_b32 s18, 0x2100000
	v_mad_u64_u32 v[30:31], s[4:5], v0, s18, v[30:31]
	v_mov_b32_e32 v0, v31
	v_lshrrev_b32_e32 v31, 12, v35
	v_lshlrev_b64 v[36:37], 11, v[34:35]
	v_mad_u64_u32 v[32:33], s[4:5], v31, s18, v[0:1]
	v_mov_b32_e32 v31, v32
	v_and_b32_e32 v0, 0x7ff800, v36
	v_lshl_add_u64 v[30:31], v[30:31], 0, v[0:1]
	v_and_b32_e32 v32, 0xff800000, v36
	v_mov_b32_e32 v33, v37
	v_lshl_add_u64 v[30:31], v[108:109], 2, v[30:31]
	s_mov_b32 s4, 0x8381000
	v_lshl_add_u64 v[32:33], s[58:59], 0, v[32:33]
	v_lshl_add_u64 v[14:15], v[118:119], 0, v[36:37]
	v_lshl_add_u64 v[18:19], v[120:121], 0, v[36:37]
	v_lshl_add_u64 v[22:23], v[122:123], 0, v[36:37]
	v_add_co_u32_e32 v30, vcc, s4, v30
	v_mad_u64_u32 v[32:33], s[4:5], v34, s67, v[32:33]
	v_lshl_add_u64 v[36:37], v[36:37], 0, s[82:83]
	v_mad_i32_i24 v33, v35, s67, v33
	v_and_b32_e32 v36, 0xff800000, v36
	v_addc_co_u32_e32 v31, vcc, 0, v31, vcc
	v_lshl_add_u64 v[38:39], v[32:33], 0, v[110:111]
	v_lshl_add_u64 v[36:37], s[58:59], 0, v[36:37]
	global_load_dwordx4 v[14:17], v[14:15], off
	s_nop 0
	global_load_dwordx4 v[18:21], v[18:19], off
	s_nop 0
	global_load_dwordx4 v[22:25], v[22:23], off
	s_nop 0
	global_load_dwordx4 v[30:33], v[30:31], off offset:1024
	s_nop 0
	global_load_dwordx2 v[140:141], v[38:39], off offset:2560
	v_add_co_u32_e32 v38, vcc, s15, v38
	v_mad_u64_u32 v[36:37], s[4:5], v34, s67, v[36:37]
	s_nop 0
	v_addc_co_u32_e32 v39, vcc, 0, v39, vcc
	v_mad_i32_i24 v37, v35, s67, v37
	v_lshl_add_u64 v[34:35], v[36:37], 0, v[110:111]
	global_load_dwordx2 v[144:145], v[38:39], off offset:512
	global_load_dwordx2 v[146:147], v[34:35], off offset:-3840
	global_load_dwordx2 v[148:149], v[34:35], off offset:-1792
